# attention phase: the 16 context windowed-GQA units run on workgroups 240..255 (whose own windowed-GQA unit is two key tiles shorter) instead of 16..31; otherwise as v83
# speedup vs baseline: 1.0064x; 1.0016x over previous
; __global__ void __launch_bounds__(NTHR, 2) mk_fwd(Args args) {
;     ...
;                 for (int L = bid; L < (rep == 0 ? 544 : 256); L += G) {
;                     const int npass = (PROBE_AA && L >= 256 && L < 768) ? 2 : 1;
;                     for (int pass = 0; pass < npass; ++pass) {
;                     if ((ASEL & 1) && L < 256) { const int bh_ = (L & 7) + 8 * ((L >> 3) & 1), b = bh_ >> 3, h = bh_ & 7, qs = L >> 4;
;                         attn_unit<96, false, 4>(lds, (const bf16_t*)(ws + O_QB) + (size_t)b * TB * 768 + h * 96, 768, (const bf16_t*)(ws + O_KB) + (size_t)b * TB * 768 + h * 96, 768,
;                                              (const bf16_t*)(ws + O_VBT) + (size_t)(b * 8 + h) * 64 * TB, (bf16_t*)(ws + O_YB) + (size_t)b * TB * 512 + h * 64, 512, LC + qs * 512, 0, 132, 0, 0, 0.f, false);
;                     } else if ((ASEL & 2) && L >= 256 && L < 512) { const int L2 = L - 256, bh_ = (L2 & 7) + 8 * ((L2 >> 3) & 1), b = bh_ >> 3, h = bh_ & 7, qs = L2 >> 4, kvh = h >> 2;
;                         const int p0 = qs * 512, lo = (p0 - 128 < 0) ? 0 : p0 - 128, hi = (p0 + 640 > SEQ) ? SEQ : p0 + 640;
;                         bf16_t* qo = (bf16_t*)(ws + O_QA) + (size_t)b * TB * 512 + h * 64;
;                         attn_unit<64, true, 4>(lds, qo, 512, (const bf16_t*)(ws + O_KA) + (size_t)b * TB * 128 + kvh * 64, 128, (const bf16_t*)(ws + O_VAT) + (size_t)(b * 2 + kvh) * 64 * TB,
;                                             qo, 512, LC + p0, 0, 4, (lo + LC) / 64, (hi - lo) / 64, ap->in[I_SINK][l * 8 + h] * LOG2E, true);
;                     } else if ((ASEL & 4) && L >= 512 && L < 528) { const int L2 = L - 512, b = L2 >> 3, h = L2 & 7;
;                         attn_unit<96, false, 2>(lds, (const bf16_t*)(ws + O_QB) + (size_t)b * TB * 768 + h * 96, 768, (const bf16_t*)(ws + O_KB) + (size_t)b * TB * 768 + h * 96, 768,
;                                              (const bf16_t*)(ws + O_VBT) + (size_t)(b * 8 + h) * 64 * TB, (bf16_t*)(ws + O_YB) + (size_t)b * TB * 512 + h * 64, 512, 0, 0, 4, 0, 0, 0.f, false);
;                     } else if ((ASEL & 8) && L >= 528) { const int L2 = L - 528, b = L2 >> 3, h = L2 & 7, kvh = h >> 2;
;                         bf16_t* qo = (bf16_t*)(ws + O_QA) + (size_t)b * TB * 512 + h * 64;
.LBB0_406:
	s_add_i32 s69, s69, s97
	s_sub_i32 s99, s69, 224
	s_sub_i32 s98, s69, 752
	s_cmp_lt_u32 s98, 16
	s_cselect_b32 s99, s99, s69
	s_sub_i32 s98, s69, 528
	s_cmp_lt_u32 s98, 16
	s_cselect_b32 s69, 0x7fff, s99
	v_cvt_pk_bf16_f32 v1, v2, v3
	global_store_dwordx2 v[18:19], v[0:1], off offset:96
	v_readlane_b32 s0, v254, 27
	s_movk_i32 s1, 0x21f
	s_nop 2
	s_cmp_eq_u32 s0, 3
	s_cselect_b32 s0, 0x1ff, s1
	s_cmp_gt_i32 s69, s0
	s_cbranch_scc1 .LBB0_506
